# attention: cross-slot LDS prefetch (next half K fragments after QK, next PV V fragments as registers free)
# speedup vs baseline: 1.1004x; 1.0056x over previous
.Lpa_comp_0:
	s_cmp_eq_u32 s54, 1
	s_cbranch_scc0 .Lpa_pend_0
	ds_read_b128 v[96:99], v191 offset:0
	ds_read_b128 v[100:103], v190 offset:0
	ds_read_b128 v[104:107], v189 offset:0
	ds_read_b128 v[108:111], v188 offset:0
	s_waitcnt lgkmcnt(3)
	v_mfma_f32_32x32x16_bf16 v[64:79], v[96:99], v[156:159], 0
	s_waitcnt lgkmcnt(2)
	v_mfma_f32_32x32x16_bf16 v[64:79], v[100:103], v[152:155], v[64:79]
	s_waitcnt lgkmcnt(1)
	v_mfma_f32_32x32x16_bf16 v[64:79], v[104:107], v[148:151], v[64:79]
	s_waitcnt lgkmcnt(0)
	v_mfma_f32_32x32x16_bf16 v[64:79], v[108:111], v[144:147], v[64:79]
	ds_read_b128 v[96:99], v191 offset:8192
	ds_read_b128 v[100:103], v190 offset:8192
	ds_read_b128 v[104:107], v189 offset:8192
	ds_read_b128 v[108:111], v188 offset:8192
	ds_read_b64_tr_b16 v[112:113], v172 offset:0
	ds_read_b64_tr_b16 v[114:115], v192 offset:0
	ds_read_b64_tr_b16 v[116:117], v173 offset:0
	ds_read_b64_tr_b16 v[118:119], v193 offset:0
	ds_read_b64_tr_b16 v[120:121], v174 offset:0
	ds_read_b64_tr_b16 v[122:123], v194 offset:0
	ds_read_b64_tr_b16 v[124:125], v175 offset:0
	ds_read_b64_tr_b16 v[126:127], v197 offset:0
	s_cmp_lt_i32 s54, s29
	s_cbranch_scc0 .Lpa_nv_0a
	s_add_i32 m0, s38, 0x10000
	s_nop 0
	global_load_lds_dwordx4 v166, s[58:59]
	s_add_i32 m0, s57, 0x10000
	s_nop 0
	global_load_lds_dwordx4 v170, s[58:59]
	s_add_u32 s58, s58, 0x10000
	s_addc_u32 s59, s59, 0

.Lpa_nk_0a:
	v_exp_f32_e32 v64, v64
	v_exp_f32_e32 v65, v65
	v_exp_f32_e32 v66, v66
	v_exp_f32_e32 v67, v67
	v_pk_add_f32 v[198:199], v[198:199], v[64:65]
	v_pk_add_f32 v[200:201], v[200:201], v[66:67]
	v_exp_f32_e32 v68, v68
	v_exp_f32_e32 v69, v69
	v_exp_f32_e32 v70, v70
	v_exp_f32_e32 v71, v71
	v_pk_add_f32 v[198:199], v[198:199], v[68:69]
	v_pk_add_f32 v[200:201], v[200:201], v[70:71]
	v_exp_f32_e32 v72, v72
	v_exp_f32_e32 v73, v73
	v_exp_f32_e32 v74, v74
	v_exp_f32_e32 v75, v75
	v_pk_add_f32 v[198:199], v[198:199], v[72:73]
	v_pk_add_f32 v[200:201], v[200:201], v[74:75]
	v_exp_f32_e32 v76, v76
	v_exp_f32_e32 v77, v77
	v_exp_f32_e32 v78, v78
	v_exp_f32_e32 v79, v79
	v_pk_add_f32 v[198:199], v[198:199], v[76:77]
	v_pk_add_f32 v[200:201], v[200:201], v[78:79]
	v_cvt_pk_bf16_f32 v80, v64, v65
	v_cvt_pk_bf16_f32 v81, v66, v67
	v_cvt_pk_bf16_f32 v82, v68, v69
	v_cvt_pk_bf16_f32 v83, v70, v71
	v_cvt_pk_bf16_f32 v84, v72, v73
	v_cvt_pk_bf16_f32 v85, v74, v75
	v_cvt_pk_bf16_f32 v86, v76, v77
	v_cvt_pk_bf16_f32 v87, v78, v79
	s_branch .Lpa_h1_0
.Lpa_pend_0:
	ds_read_b128 v[96:99], v191 offset:0
	ds_read_b128 v[100:103], v190 offset:0
	ds_read_b128 v[104:107], v189 offset:0
	ds_read_b128 v[108:111], v188 offset:0
	s_waitcnt lgkmcnt(3)
	v_mfma_f32_32x32x16_bf16 v[64:79], v[96:99], v[156:159], 0
	s_waitcnt lgkmcnt(2)
	v_mfma_f32_32x32x16_bf16 v[64:79], v[100:103], v[152:155], v[64:79]
	s_waitcnt lgkmcnt(1)
	v_mfma_f32_32x32x16_bf16 v[64:79], v[104:107], v[148:151], v[64:79]
	s_waitcnt lgkmcnt(0)
	v_mfma_f32_32x32x16_bf16 v[64:79], v[108:111], v[144:147], v[64:79]
	ds_read_b128 v[96:99], v191 offset:8192
	ds_read_b128 v[100:103], v190 offset:8192
	ds_read_b128 v[104:107], v189 offset:8192
	ds_read_b128 v[108:111], v188 offset:8192
	v_mfma_f32_32x32x16_bf16 v[0:15], v[88:91], v[112:115], v[0:15]
	ds_read_b64_tr_b16 v[112:113], v172 offset:45056
	ds_read_b64_tr_b16 v[114:115], v192 offset:45056
	s_cmp_lt_i32 s54, s29
	s_cbranch_scc0 .Lpa_nv_0b
	s_add_i32 m0, s38, 0x10000
	s_nop 0
	global_load_lds_dwordx4 v166, s[58:59]
	s_add_i32 m0, s57, 0x10000
	s_nop 0
	global_load_lds_dwordx4 v170, s[58:59]
	s_add_u32 s58, s58, 0x10000
	s_addc_u32 s59, s59, 0
.Lpa_nv_0b:
	v_mfma_f32_32x32x16_bf16 v[16:31], v[88:91], v[116:119], v[16:31]
	ds_read_b64_tr_b16 v[116:117], v173 offset:45056
	ds_read_b64_tr_b16 v[118:119], v193 offset:45056
	s_cmp_gt_i32 s54, s53
	s_cbranch_scc1 .Lpa_nk_0b
	s_add_i32 m0, s38, 0x8000
	s_nop 0
	global_load_lds_dwordx4 v166, s[24:25]
	s_add_i32 m0, s57, 0x8000
	s_nop 0
	global_load_lds_dwordx4 v170, s[24:25]
	s_add_u32 s24, s24, 0x10000
	s_addc_u32 s25, s25, 0
.Lpa_nk_0b:
	v_mfma_f32_32x32x16_bf16 v[32:47], v[88:91], v[120:123], v[32:47]
	ds_read_b64_tr_b16 v[120:121], v174 offset:45056
	ds_read_b64_tr_b16 v[122:123], v194 offset:45056
	v_exp_f32_e32 v64, v64
	v_exp_f32_e32 v65, v65
	v_exp_f32_e32 v66, v66
	v_exp_f32_e32 v67, v67
	v_pk_add_f32 v[198:199], v[198:199], v[64:65]
	v_pk_add_f32 v[200:201], v[200:201], v[66:67]
	v_mfma_f32_32x32x16_bf16 v[48:63], v[88:91], v[124:127], v[48:63]
	ds_read_b64_tr_b16 v[124:125], v175 offset:45056
	ds_read_b64_tr_b16 v[126:127], v197 offset:45056
	v_exp_f32_e32 v68, v68
	v_exp_f32_e32 v69, v69
	v_exp_f32_e32 v70, v70
	v_exp_f32_e32 v71, v71
	v_pk_add_f32 v[198:199], v[198:199], v[68:69]
	v_pk_add_f32 v[200:201], v[200:201], v[70:71]
	s_waitcnt lgkmcnt(6)
	v_mfma_f32_32x32x16_bf16 v[0:15], v[92:95], v[112:115], v[0:15]
	ds_read_b64_tr_b16 v[112:113], v172 offset:0
	ds_read_b64_tr_b16 v[114:115], v192 offset:0
	v_exp_f32_e32 v72, v72
	v_exp_f32_e32 v73, v73
	v_exp_f32_e32 v74, v74
	v_exp_f32_e32 v75, v75
	v_pk_add_f32 v[198:199], v[198:199], v[72:73]
	v_pk_add_f32 v[200:201], v[200:201], v[74:75]
	s_waitcnt lgkmcnt(6)
	v_mfma_f32_32x32x16_bf16 v[16:31], v[92:95], v[116:119], v[16:31]
	ds_read_b64_tr_b16 v[116:117], v173 offset:0
	ds_read_b64_tr_b16 v[118:119], v193 offset:0
	v_exp_f32_e32 v76, v76
	v_exp_f32_e32 v77, v77
	v_exp_f32_e32 v78, v78
	v_exp_f32_e32 v79, v79
	v_pk_add_f32 v[198:199], v[198:199], v[76:77]
	v_pk_add_f32 v[200:201], v[200:201], v[78:79]
	s_waitcnt lgkmcnt(6)
	v_mfma_f32_32x32x16_bf16 v[32:47], v[92:95], v[120:123], v[32:47]
	ds_read_b64_tr_b16 v[120:121], v174 offset:0
	ds_read_b64_tr_b16 v[122:123], v194 offset:0
	v_cvt_pk_bf16_f32 v80, v64, v65
	v_cvt_pk_bf16_f32 v81, v66, v67
	v_cvt_pk_bf16_f32 v82, v68, v69
	v_cvt_pk_bf16_f32 v83, v70, v71
	s_waitcnt lgkmcnt(6)
	v_mfma_f32_32x32x16_bf16 v[48:63], v[92:95], v[124:127], v[48:63]
	ds_read_b64_tr_b16 v[124:125], v175 offset:0
	ds_read_b64_tr_b16 v[126:127], v197 offset:0
	v_cvt_pk_bf16_f32 v84, v72, v73
	v_cvt_pk_bf16_f32 v85, v74, v75
	v_cvt_pk_bf16_f32 v86, v76, v77
	v_cvt_pk_bf16_f32 v87, v78, v79
.Lpa_h1_0:
	s_waitcnt lgkmcnt(11)
	v_mfma_f32_32x32x16_bf16 v[64:79], v[96:99], v[156:159], 0
	s_waitcnt lgkmcnt(10)
	v_mfma_f32_32x32x16_bf16 v[64:79], v[100:103], v[152:155], v[64:79]
	s_waitcnt lgkmcnt(9)
	v_mfma_f32_32x32x16_bf16 v[64:79], v[104:107], v[148:151], v[64:79]
	s_waitcnt lgkmcnt(8)
	v_mfma_f32_32x32x16_bf16 v[64:79], v[108:111], v[144:147], v[64:79]
	s_waitcnt lgkmcnt(6)
	v_mfma_f32_32x32x16_bf16 v[0:15], v[80:83], v[112:115], v[0:15]
	ds_read_b64_tr_b16 v[112:113], v172 offset:4096
	ds_read_b64_tr_b16 v[114:115], v192 offset:4096
	s_waitcnt lgkmcnt(6)
	v_mfma_f32_32x32x16_bf16 v[16:31], v[80:83], v[116:119], v[16:31]
	ds_read_b64_tr_b16 v[116:117], v173 offset:4096
	ds_read_b64_tr_b16 v[118:119], v193 offset:4096
	s_waitcnt lgkmcnt(6)
	v_mfma_f32_32x32x16_bf16 v[32:47], v[80:83], v[120:123], v[32:47]
	ds_read_b64_tr_b16 v[120:121], v174 offset:4096
	ds_read_b64_tr_b16 v[122:123], v194 offset:4096
	v_exp_f32_e32 v64, v64
	v_exp_f32_e32 v65, v65
	v_exp_f32_e32 v66, v66
	v_exp_f32_e32 v67, v67
	v_pk_add_f32 v[198:199], v[198:199], v[64:65]
	v_pk_add_f32 v[200:201], v[200:201], v[66:67]
	s_waitcnt lgkmcnt(6)
	v_mfma_f32_32x32x16_bf16 v[48:63], v[80:83], v[124:127], v[48:63]
	ds_read_b64_tr_b16 v[124:125], v175 offset:4096
	ds_read_b64_tr_b16 v[126:127], v197 offset:4096
	v_exp_f32_e32 v68, v68
	v_exp_f32_e32 v69, v69
	v_exp_f32_e32 v70, v70
	v_exp_f32_e32 v71, v71
	v_pk_add_f32 v[198:199], v[198:199], v[68:69]
	v_pk_add_f32 v[200:201], v[200:201], v[70:71]
	s_waitcnt lgkmcnt(6)
	v_mfma_f32_32x32x16_bf16 v[0:15], v[84:87], v[112:115], v[0:15]
	ds_read_b64_tr_b16 v[112:113], v172 offset:8192
	ds_read_b64_tr_b16 v[114:115], v192 offset:8192
	v_exp_f32_e32 v72, v72
	v_exp_f32_e32 v73, v73
	v_exp_f32_e32 v74, v74
	v_exp_f32_e32 v75, v75
	v_pk_add_f32 v[198:199], v[198:199], v[72:73]
	v_pk_add_f32 v[200:201], v[200:201], v[74:75]
	s_waitcnt lgkmcnt(6)
	v_mfma_f32_32x32x16_bf16 v[16:31], v[84:87], v[116:119], v[16:31]
	ds_read_b64_tr_b16 v[116:117], v173 offset:8192
	ds_read_b64_tr_b16 v[118:119], v193 offset:8192
	v_exp_f32_e32 v76, v76
	v_exp_f32_e32 v77, v77
	v_exp_f32_e32 v78, v78
	v_exp_f32_e32 v79, v79
	v_pk_add_f32 v[198:199], v[198:199], v[76:77]
	v_pk_add_f32 v[200:201], v[200:201], v[78:79]
	s_waitcnt lgkmcnt(6)
	v_mfma_f32_32x32x16_bf16 v[32:47], v[84:87], v[120:123], v[32:47]
	ds_read_b64_tr_b16 v[120:121], v174 offset:8192
	ds_read_b64_tr_b16 v[122:123], v194 offset:8192
	v_cvt_pk_bf16_f32 v88, v64, v65
	v_cvt_pk_bf16_f32 v89, v66, v67
	v_cvt_pk_bf16_f32 v90, v68, v69
	v_cvt_pk_bf16_f32 v91, v70, v71
	s_waitcnt lgkmcnt(6)
	v_mfma_f32_32x32x16_bf16 v[48:63], v[84:87], v[124:127], v[48:63]
	ds_read_b64_tr_b16 v[124:125], v175 offset:8192
	ds_read_b64_tr_b16 v[126:127], v197 offset:8192
	v_cvt_pk_bf16_f32 v92, v72, v73
	v_cvt_pk_bf16_f32 v93, v74, v75
	v_cvt_pk_bf16_f32 v94, v76, v77
	v_cvt_pk_bf16_f32 v95, v78, v79
	s_cmp_lt_i32 s54, vcc_lo
	s_cbranch_scc1 .Lpa_next_0
	s_nop 1
	s_waitcnt lgkmcnt(6)
	v_mfma_f32_32x32x16_bf16 v[0:15], v[88:91], v[112:115], v[0:15]
	ds_read_b64_tr_b16 v[112:113], v172 offset:12288
	ds_read_b64_tr_b16 v[114:115], v192 offset:12288
	s_waitcnt lgkmcnt(6)
	v_mfma_f32_32x32x16_bf16 v[16:31], v[88:91], v[116:119], v[16:31]
	ds_read_b64_tr_b16 v[116:117], v173 offset:12288
	ds_read_b64_tr_b16 v[118:119], v193 offset:12288
	s_waitcnt lgkmcnt(6)
	v_mfma_f32_32x32x16_bf16 v[32:47], v[88:91], v[120:123], v[32:47]
	ds_read_b64_tr_b16 v[120:121], v174 offset:12288
	ds_read_b64_tr_b16 v[122:123], v194 offset:12288
	s_waitcnt lgkmcnt(6)
	v_mfma_f32_32x32x16_bf16 v[48:63], v[88:91], v[124:127], v[48:63]
	ds_read_b64_tr_b16 v[124:125], v175 offset:12288
	ds_read_b64_tr_b16 v[126:127], v197 offset:12288
	s_waitcnt lgkmcnt(6)
	v_mfma_f32_32x32x16_bf16 v[0:15], v[92:95], v[112:115], v[0:15]
	s_waitcnt lgkmcnt(4)
	v_mfma_f32_32x32x16_bf16 v[16:31], v[92:95], v[116:119], v[16:31]
	s_waitcnt lgkmcnt(2)
	v_mfma_f32_32x32x16_bf16 v[32:47], v[92:95], v[120:123], v[32:47]
	s_waitcnt lgkmcnt(0)
	v_mfma_f32_32x32x16_bf16 v[48:63], v[92:95], v[124:127], v[48:63]

.Lpa_comp_1:
	ds_read_b128 v[96:99], v191 offset:16384
	ds_read_b128 v[100:103], v190 offset:16384
	ds_read_b128 v[104:107], v189 offset:16384
	ds_read_b128 v[108:111], v188 offset:16384
	s_waitcnt lgkmcnt(3)
	v_mfma_f32_32x32x16_bf16 v[64:79], v[96:99], v[156:159], 0
	s_waitcnt lgkmcnt(2)
	v_mfma_f32_32x32x16_bf16 v[64:79], v[100:103], v[152:155], v[64:79]
	s_waitcnt lgkmcnt(1)
	v_mfma_f32_32x32x16_bf16 v[64:79], v[104:107], v[148:151], v[64:79]
	s_waitcnt lgkmcnt(0)
	v_mfma_f32_32x32x16_bf16 v[64:79], v[108:111], v[144:147], v[64:79]
	ds_read_b128 v[96:99], v191 offset:24576
	ds_read_b128 v[100:103], v190 offset:24576
	ds_read_b128 v[104:107], v189 offset:24576
	ds_read_b128 v[108:111], v188 offset:24576
	v_mfma_f32_32x32x16_bf16 v[0:15], v[88:91], v[112:115], v[0:15]
	ds_read_b64_tr_b16 v[112:113], v172 offset:12288
	ds_read_b64_tr_b16 v[114:115], v192 offset:12288
	s_cmp_lt_i32 s54, s29
	s_cbranch_scc0 .Lpa_nv_1b
	s_add_i32 m0, s38, 0x14000
	s_nop 0
	global_load_lds_dwordx4 v166, s[58:59]
	s_add_i32 m0, s57, 0x14000
	s_nop 0
	global_load_lds_dwordx4 v170, s[58:59]
	s_add_u32 s58, s58, 0x10000
	s_addc_u32 s59, s59, 0
.Lpa_nv_1b:
	v_mfma_f32_32x32x16_bf16 v[16:31], v[88:91], v[116:119], v[16:31]
	ds_read_b64_tr_b16 v[116:117], v173 offset:12288
	ds_read_b64_tr_b16 v[118:119], v193 offset:12288
	s_cmp_gt_i32 s54, s53
	s_cbranch_scc1 .Lpa_nk_1b
	s_add_i32 m0, s38, 0x0
	s_nop 0
	global_load_lds_dwordx4 v166, s[24:25]
	s_add_i32 m0, s57, 0x0
	s_nop 0
	global_load_lds_dwordx4 v170, s[24:25]
	s_add_u32 s24, s24, 0x10000
	s_addc_u32 s25, s25, 0
.Lpa_nk_1b:
	v_mfma_f32_32x32x16_bf16 v[32:47], v[88:91], v[120:123], v[32:47]
	ds_read_b64_tr_b16 v[120:121], v174 offset:12288
	ds_read_b64_tr_b16 v[122:123], v194 offset:12288
	v_exp_f32_e32 v64, v64
	v_exp_f32_e32 v65, v65
	v_exp_f32_e32 v66, v66
	v_exp_f32_e32 v67, v67
	v_pk_add_f32 v[198:199], v[198:199], v[64:65]
	v_pk_add_f32 v[200:201], v[200:201], v[66:67]
	v_mfma_f32_32x32x16_bf16 v[48:63], v[88:91], v[124:127], v[48:63]
	ds_read_b64_tr_b16 v[124:125], v175 offset:12288
	ds_read_b64_tr_b16 v[126:127], v197 offset:12288
	v_exp_f32_e32 v68, v68
	v_exp_f32_e32 v69, v69
	v_exp_f32_e32 v70, v70
	v_exp_f32_e32 v71, v71
	v_pk_add_f32 v[198:199], v[198:199], v[68:69]
	v_pk_add_f32 v[200:201], v[200:201], v[70:71]
	s_waitcnt lgkmcnt(6)
	v_mfma_f32_32x32x16_bf16 v[0:15], v[92:95], v[112:115], v[0:15]
	ds_read_b64_tr_b16 v[112:113], v172 offset:16384
	ds_read_b64_tr_b16 v[114:115], v192 offset:16384
	v_exp_f32_e32 v72, v72
	v_exp_f32_e32 v73, v73
	v_exp_f32_e32 v74, v74
	v_exp_f32_e32 v75, v75
	v_pk_add_f32 v[198:199], v[198:199], v[72:73]
	v_pk_add_f32 v[200:201], v[200:201], v[74:75]
	s_waitcnt lgkmcnt(6)
	v_mfma_f32_32x32x16_bf16 v[16:31], v[92:95], v[116:119], v[16:31]
	ds_read_b64_tr_b16 v[116:117], v173 offset:16384
	ds_read_b64_tr_b16 v[118:119], v193 offset:16384
	v_exp_f32_e32 v76, v76
	v_exp_f32_e32 v77, v77
	v_exp_f32_e32 v78, v78
	v_exp_f32_e32 v79, v79
	v_pk_add_f32 v[198:199], v[198:199], v[76:77]
	v_pk_add_f32 v[200:201], v[200:201], v[78:79]
	s_waitcnt lgkmcnt(6)
	v_mfma_f32_32x32x16_bf16 v[32:47], v[92:95], v[120:123], v[32:47]
	ds_read_b64_tr_b16 v[120:121], v174 offset:16384
	ds_read_b64_tr_b16 v[122:123], v194 offset:16384
	v_cvt_pk_bf16_f32 v80, v64, v65
	v_cvt_pk_bf16_f32 v81, v66, v67
	v_cvt_pk_bf16_f32 v82, v68, v69
	v_cvt_pk_bf16_f32 v83, v70, v71
	s_waitcnt lgkmcnt(6)
	v_mfma_f32_32x32x16_bf16 v[48:63], v[92:95], v[124:127], v[48:63]
	ds_read_b64_tr_b16 v[124:125], v175 offset:16384
	ds_read_b64_tr_b16 v[126:127], v197 offset:16384
	v_cvt_pk_bf16_f32 v84, v72, v73
	v_cvt_pk_bf16_f32 v85, v74, v75
	v_cvt_pk_bf16_f32 v86, v76, v77
	v_cvt_pk_bf16_f32 v87, v78, v79
.Lpa_h1_1:
	s_waitcnt lgkmcnt(11)
	v_mfma_f32_32x32x16_bf16 v[64:79], v[96:99], v[156:159], 0
	s_waitcnt lgkmcnt(10)
	v_mfma_f32_32x32x16_bf16 v[64:79], v[100:103], v[152:155], v[64:79]
	s_waitcnt lgkmcnt(9)
	v_mfma_f32_32x32x16_bf16 v[64:79], v[104:107], v[148:151], v[64:79]
	s_waitcnt lgkmcnt(8)
	v_mfma_f32_32x32x16_bf16 v[64:79], v[108:111], v[144:147], v[64:79]
	s_waitcnt lgkmcnt(6)
	v_mfma_f32_32x32x16_bf16 v[0:15], v[80:83], v[112:115], v[0:15]
	ds_read_b64_tr_b16 v[112:113], v172 offset:20480
	ds_read_b64_tr_b16 v[114:115], v192 offset:20480
	s_waitcnt lgkmcnt(6)
	v_mfma_f32_32x32x16_bf16 v[16:31], v[80:83], v[116:119], v[16:31]
	ds_read_b64_tr_b16 v[116:117], v173 offset:20480
	ds_read_b64_tr_b16 v[118:119], v193 offset:20480
	s_waitcnt lgkmcnt(6)
	v_mfma_f32_32x32x16_bf16 v[32:47], v[80:83], v[120:123], v[32:47]
	ds_read_b64_tr_b16 v[120:121], v174 offset:20480
	ds_read_b64_tr_b16 v[122:123], v194 offset:20480
	v_exp_f32_e32 v64, v64
	v_exp_f32_e32 v65, v65
	v_exp_f32_e32 v66, v66
	v_exp_f32_e32 v67, v67
	v_pk_add_f32 v[198:199], v[198:199], v[64:65]
	v_pk_add_f32 v[200:201], v[200:201], v[66:67]
	s_waitcnt lgkmcnt(6)
	v_mfma_f32_32x32x16_bf16 v[48:63], v[80:83], v[124:127], v[48:63]
	ds_read_b64_tr_b16 v[124:125], v175 offset:20480
	ds_read_b64_tr_b16 v[126:127], v197 offset:20480
	v_exp_f32_e32 v68, v68
	v_exp_f32_e32 v69, v69
	v_exp_f32_e32 v70, v70
	v_exp_f32_e32 v71, v71
	v_pk_add_f32 v[198:199], v[198:199], v[68:69]
	v_pk_add_f32 v[200:201], v[200:201], v[70:71]
	s_waitcnt lgkmcnt(6)
	v_mfma_f32_32x32x16_bf16 v[0:15], v[84:87], v[112:115], v[0:15]
	ds_read_b64_tr_b16 v[112:113], v172 offset:24576
	ds_read_b64_tr_b16 v[114:115], v192 offset:24576
	v_exp_f32_e32 v72, v72
	v_exp_f32_e32 v73, v73
	v_exp_f32_e32 v74, v74
	v_exp_f32_e32 v75, v75
	v_pk_add_f32 v[198:199], v[198:199], v[72:73]
	v_pk_add_f32 v[200:201], v[200:201], v[74:75]
	s_waitcnt lgkmcnt(6)
	v_mfma_f32_32x32x16_bf16 v[16:31], v[84:87], v[116:119], v[16:31]
	ds_read_b64_tr_b16 v[116:117], v173 offset:24576
	ds_read_b64_tr_b16 v[118:119], v193 offset:24576
	v_exp_f32_e32 v76, v76
	v_exp_f32_e32 v77, v77
	v_exp_f32_e32 v78, v78
	v_exp_f32_e32 v79, v79
	v_pk_add_f32 v[198:199], v[198:199], v[76:77]
	v_pk_add_f32 v[200:201], v[200:201], v[78:79]
	s_waitcnt lgkmcnt(6)
	v_mfma_f32_32x32x16_bf16 v[32:47], v[84:87], v[120:123], v[32:47]
	ds_read_b64_tr_b16 v[120:121], v174 offset:24576
	ds_read_b64_tr_b16 v[122:123], v194 offset:24576
	v_cvt_pk_bf16_f32 v88, v64, v65
	v_cvt_pk_bf16_f32 v89, v66, v67
	v_cvt_pk_bf16_f32 v90, v68, v69
	v_cvt_pk_bf16_f32 v91, v70, v71
	s_waitcnt lgkmcnt(6)
	v_mfma_f32_32x32x16_bf16 v[48:63], v[84:87], v[124:127], v[48:63]
	ds_read_b64_tr_b16 v[124:125], v175 offset:24576
	ds_read_b64_tr_b16 v[126:127], v197 offset:24576
	v_cvt_pk_bf16_f32 v92, v72, v73
	v_cvt_pk_bf16_f32 v93, v74, v75
	v_cvt_pk_bf16_f32 v94, v76, v77
	v_cvt_pk_bf16_f32 v95, v78, v79
	s_cmp_lt_i32 s54, vcc_lo
	s_cbranch_scc1 .Lpa_next_1
	s_nop 1
	s_waitcnt lgkmcnt(6)
	v_mfma_f32_32x32x16_bf16 v[0:15], v[88:91], v[112:115], v[0:15]
	ds_read_b64_tr_b16 v[112:113], v172 offset:28672
	ds_read_b64_tr_b16 v[114:115], v192 offset:28672
	s_waitcnt lgkmcnt(6)
	v_mfma_f32_32x32x16_bf16 v[16:31], v[88:91], v[116:119], v[16:31]
	ds_read_b64_tr_b16 v[116:117], v173 offset:28672
	ds_read_b64_tr_b16 v[118:119], v193 offset:28672
	s_waitcnt lgkmcnt(6)
	v_mfma_f32_32x32x16_bf16 v[32:47], v[88:91], v[120:123], v[32:47]
	ds_read_b64_tr_b16 v[120:121], v174 offset:28672
	ds_read_b64_tr_b16 v[122:123], v194 offset:28672
	s_waitcnt lgkmcnt(6)
	v_mfma_f32_32x32x16_bf16 v[48:63], v[88:91], v[124:127], v[48:63]
	ds_read_b64_tr_b16 v[124:125], v175 offset:28672
	ds_read_b64_tr_b16 v[126:127], v197 offset:28672
	s_waitcnt lgkmcnt(6)
	v_mfma_f32_32x32x16_bf16 v[0:15], v[92:95], v[112:115], v[0:15]
	s_waitcnt lgkmcnt(4)
	v_mfma_f32_32x32x16_bf16 v[16:31], v[92:95], v[116:119], v[16:31]
	s_waitcnt lgkmcnt(2)
	v_mfma_f32_32x32x16_bf16 v[32:47], v[92:95], v[120:123], v[32:47]
	s_waitcnt lgkmcnt(0)
	v_mfma_f32_32x32x16_bf16 v[48:63], v[92:95], v[124:127], v[48:63]

.Lpa_comp_2:
	ds_read_b128 v[96:99], v191 offset:32768
	ds_read_b128 v[100:103], v190 offset:32768
	ds_read_b128 v[104:107], v189 offset:32768
	ds_read_b128 v[108:111], v188 offset:32768
	s_waitcnt lgkmcnt(3)
	v_mfma_f32_32x32x16_bf16 v[64:79], v[96:99], v[156:159], 0
	s_waitcnt lgkmcnt(2)
	v_mfma_f32_32x32x16_bf16 v[64:79], v[100:103], v[152:155], v[64:79]
	s_waitcnt lgkmcnt(1)
	v_mfma_f32_32x32x16_bf16 v[64:79], v[104:107], v[148:151], v[64:79]
	s_waitcnt lgkmcnt(0)
	v_mfma_f32_32x32x16_bf16 v[64:79], v[108:111], v[144:147], v[64:79]
	ds_read_b128 v[96:99], v191 offset:40960
	ds_read_b128 v[100:103], v190 offset:40960
	ds_read_b128 v[104:107], v189 offset:40960
	ds_read_b128 v[108:111], v188 offset:40960
	v_mfma_f32_32x32x16_bf16 v[0:15], v[88:91], v[112:115], v[0:15]
	ds_read_b64_tr_b16 v[112:113], v172 offset:28672
	ds_read_b64_tr_b16 v[114:115], v192 offset:28672
	s_cmp_lt_i32 s54, s29
	s_cbranch_scc0 .Lpa_nv_2b
	s_add_i32 m0, s38, 0xc000
	s_nop 0
	global_load_lds_dwordx4 v166, s[58:59]
	s_add_i32 m0, s57, 0xc000
	s_nop 0
	global_load_lds_dwordx4 v170, s[58:59]
	s_add_u32 s58, s58, 0x10000
	s_addc_u32 s59, s59, 0
.Lpa_nv_2b:
	v_mfma_f32_32x32x16_bf16 v[16:31], v[88:91], v[116:119], v[16:31]
	ds_read_b64_tr_b16 v[116:117], v173 offset:28672
	ds_read_b64_tr_b16 v[118:119], v193 offset:28672
	s_cmp_gt_i32 s54, s53
	s_cbranch_scc1 .Lpa_nk_2b
	s_add_i32 m0, s38, 0x4000
	s_nop 0
	global_load_lds_dwordx4 v166, s[24:25]
	s_add_i32 m0, s57, 0x4000
	s_nop 0
	global_load_lds_dwordx4 v170, s[24:25]
	s_add_u32 s24, s24, 0x10000
	s_addc_u32 s25, s25, 0
.Lpa_nk_2b:
	v_mfma_f32_32x32x16_bf16 v[32:47], v[88:91], v[120:123], v[32:47]
	ds_read_b64_tr_b16 v[120:121], v174 offset:28672
	ds_read_b64_tr_b16 v[122:123], v194 offset:28672
	v_exp_f32_e32 v64, v64
	v_exp_f32_e32 v65, v65
	v_exp_f32_e32 v66, v66
	v_exp_f32_e32 v67, v67
	v_pk_add_f32 v[198:199], v[198:199], v[64:65]
	v_pk_add_f32 v[200:201], v[200:201], v[66:67]
	v_mfma_f32_32x32x16_bf16 v[48:63], v[88:91], v[124:127], v[48:63]
	ds_read_b64_tr_b16 v[124:125], v175 offset:28672
	ds_read_b64_tr_b16 v[126:127], v197 offset:28672
	v_exp_f32_e32 v68, v68
	v_exp_f32_e32 v69, v69
	v_exp_f32_e32 v70, v70
	v_exp_f32_e32 v71, v71
	v_pk_add_f32 v[198:199], v[198:199], v[68:69]
	v_pk_add_f32 v[200:201], v[200:201], v[70:71]
	s_waitcnt lgkmcnt(6)
	v_mfma_f32_32x32x16_bf16 v[0:15], v[92:95], v[112:115], v[0:15]
	ds_read_b64_tr_b16 v[112:113], v172 offset:32768
	ds_read_b64_tr_b16 v[114:115], v192 offset:32768
	v_exp_f32_e32 v72, v72
	v_exp_f32_e32 v73, v73
	v_exp_f32_e32 v74, v74
	v_exp_f32_e32 v75, v75
	v_pk_add_f32 v[198:199], v[198:199], v[72:73]
	v_pk_add_f32 v[200:201], v[200:201], v[74:75]
	s_waitcnt lgkmcnt(6)
	v_mfma_f32_32x32x16_bf16 v[16:31], v[92:95], v[116:119], v[16:31]
	ds_read_b64_tr_b16 v[116:117], v173 offset:32768
	ds_read_b64_tr_b16 v[118:119], v193 offset:32768
	v_exp_f32_e32 v76, v76
	v_exp_f32_e32 v77, v77
	v_exp_f32_e32 v78, v78
	v_exp_f32_e32 v79, v79
	v_pk_add_f32 v[198:199], v[198:199], v[76:77]
	v_pk_add_f32 v[200:201], v[200:201], v[78:79]
	s_waitcnt lgkmcnt(6)
	v_mfma_f32_32x32x16_bf16 v[32:47], v[92:95], v[120:123], v[32:47]
	ds_read_b64_tr_b16 v[120:121], v174 offset:32768
	ds_read_b64_tr_b16 v[122:123], v194 offset:32768
	v_cvt_pk_bf16_f32 v80, v64, v65
	v_cvt_pk_bf16_f32 v81, v66, v67
	v_cvt_pk_bf16_f32 v82, v68, v69
	v_cvt_pk_bf16_f32 v83, v70, v71
	s_waitcnt lgkmcnt(6)
	v_mfma_f32_32x32x16_bf16 v[48:63], v[92:95], v[124:127], v[48:63]
	ds_read_b64_tr_b16 v[124:125], v175 offset:32768
	ds_read_b64_tr_b16 v[126:127], v197 offset:32768
	v_cvt_pk_bf16_f32 v84, v72, v73
	v_cvt_pk_bf16_f32 v85, v74, v75
	v_cvt_pk_bf16_f32 v86, v76, v77
	v_cvt_pk_bf16_f32 v87, v78, v79
.Lpa_h1_2:
	s_waitcnt lgkmcnt(11)
	v_mfma_f32_32x32x16_bf16 v[64:79], v[96:99], v[156:159], 0
	s_waitcnt lgkmcnt(10)
	v_mfma_f32_32x32x16_bf16 v[64:79], v[100:103], v[152:155], v[64:79]
	s_waitcnt lgkmcnt(9)
	v_mfma_f32_32x32x16_bf16 v[64:79], v[104:107], v[148:151], v[64:79]
	s_waitcnt lgkmcnt(8)
	v_mfma_f32_32x32x16_bf16 v[64:79], v[108:111], v[144:147], v[64:79]
	s_waitcnt lgkmcnt(6)
	v_mfma_f32_32x32x16_bf16 v[0:15], v[80:83], v[112:115], v[0:15]
	ds_read_b64_tr_b16 v[112:113], v172 offset:36864
	ds_read_b64_tr_b16 v[114:115], v192 offset:36864
	s_waitcnt lgkmcnt(6)
	v_mfma_f32_32x32x16_bf16 v[16:31], v[80:83], v[116:119], v[16:31]
	ds_read_b64_tr_b16 v[116:117], v173 offset:36864
	ds_read_b64_tr_b16 v[118:119], v193 offset:36864
	s_waitcnt lgkmcnt(6)
	v_mfma_f32_32x32x16_bf16 v[32:47], v[80:83], v[120:123], v[32:47]
	ds_read_b64_tr_b16 v[120:121], v174 offset:36864
	ds_read_b64_tr_b16 v[122:123], v194 offset:36864
	v_exp_f32_e32 v64, v64
	v_exp_f32_e32 v65, v65
	v_exp_f32_e32 v66, v66
	v_exp_f32_e32 v67, v67
	v_pk_add_f32 v[198:199], v[198:199], v[64:65]
	v_pk_add_f32 v[200:201], v[200:201], v[66:67]
	s_waitcnt lgkmcnt(6)
	v_mfma_f32_32x32x16_bf16 v[48:63], v[80:83], v[124:127], v[48:63]
	ds_read_b64_tr_b16 v[124:125], v175 offset:36864
	ds_read_b64_tr_b16 v[126:127], v197 offset:36864
	v_exp_f32_e32 v68, v68
	v_exp_f32_e32 v69, v69
	v_exp_f32_e32 v70, v70
	v_exp_f32_e32 v71, v71
	v_pk_add_f32 v[198:199], v[198:199], v[68:69]
	v_pk_add_f32 v[200:201], v[200:201], v[70:71]
	s_waitcnt lgkmcnt(6)
	v_mfma_f32_32x32x16_bf16 v[0:15], v[84:87], v[112:115], v[0:15]
	ds_read_b64_tr_b16 v[112:113], v172 offset:40960
	ds_read_b64_tr_b16 v[114:115], v192 offset:40960
	v_exp_f32_e32 v72, v72
	v_exp_f32_e32 v73, v73
	v_exp_f32_e32 v74, v74
	v_exp_f32_e32 v75, v75
	v_pk_add_f32 v[198:199], v[198:199], v[72:73]
	v_pk_add_f32 v[200:201], v[200:201], v[74:75]
	s_waitcnt lgkmcnt(6)
	v_mfma_f32_32x32x16_bf16 v[16:31], v[84:87], v[116:119], v[16:31]
	ds_read_b64_tr_b16 v[116:117], v173 offset:40960
	ds_read_b64_tr_b16 v[118:119], v193 offset:40960
	v_exp_f32_e32 v76, v76
	v_exp_f32_e32 v77, v77
	v_exp_f32_e32 v78, v78
	v_exp_f32_e32 v79, v79
	v_pk_add_f32 v[198:199], v[198:199], v[76:77]
	v_pk_add_f32 v[200:201], v[200:201], v[78:79]
	s_waitcnt lgkmcnt(6)
	v_mfma_f32_32x32x16_bf16 v[32:47], v[84:87], v[120:123], v[32:47]
	ds_read_b64_tr_b16 v[120:121], v174 offset:40960
	ds_read_b64_tr_b16 v[122:123], v194 offset:40960
	v_cvt_pk_bf16_f32 v88, v64, v65
	v_cvt_pk_bf16_f32 v89, v66, v67
	v_cvt_pk_bf16_f32 v90, v68, v69
	v_cvt_pk_bf16_f32 v91, v70, v71
	s_waitcnt lgkmcnt(6)
	v_mfma_f32_32x32x16_bf16 v[48:63], v[84:87], v[124:127], v[48:63]
	ds_read_b64_tr_b16 v[124:125], v175 offset:40960
	ds_read_b64_tr_b16 v[126:127], v197 offset:40960
	v_cvt_pk_bf16_f32 v92, v72, v73
	v_cvt_pk_bf16_f32 v93, v74, v75
	v_cvt_pk_bf16_f32 v94, v76, v77
	v_cvt_pk_bf16_f32 v95, v78, v79
	s_cmp_lt_i32 s54, vcc_lo
	s_cbranch_scc1 .Lpa_next_2
	s_nop 1
	s_waitcnt lgkmcnt(6)
	v_mfma_f32_32x32x16_bf16 v[0:15], v[88:91], v[112:115], v[0:15]
	ds_read_b64_tr_b16 v[112:113], v172 offset:45056
	ds_read_b64_tr_b16 v[114:115], v192 offset:45056
	s_waitcnt lgkmcnt(6)
	v_mfma_f32_32x32x16_bf16 v[16:31], v[88:91], v[116:119], v[16:31]
	ds_read_b64_tr_b16 v[116:117], v173 offset:45056
	ds_read_b64_tr_b16 v[118:119], v193 offset:45056
	s_waitcnt lgkmcnt(6)
	v_mfma_f32_32x32x16_bf16 v[32:47], v[88:91], v[120:123], v[32:47]
	ds_read_b64_tr_b16 v[120:121], v174 offset:45056
	ds_read_b64_tr_b16 v[122:123], v194 offset:45056
	s_waitcnt lgkmcnt(6)
	v_mfma_f32_32x32x16_bf16 v[48:63], v[88:91], v[124:127], v[48:63]
	ds_read_b64_tr_b16 v[124:125], v175 offset:45056
	ds_read_b64_tr_b16 v[126:127], v197 offset:45056
	s_waitcnt lgkmcnt(6)
	v_mfma_f32_32x32x16_bf16 v[0:15], v[92:95], v[112:115], v[0:15]
	s_waitcnt lgkmcnt(4)
	v_mfma_f32_32x32x16_bf16 v[16:31], v[92:95], v[116:119], v[16:31]
	s_waitcnt lgkmcnt(2)
	v_mfma_f32_32x32x16_bf16 v[32:47], v[92:95], v[120:123], v[32:47]
	s_waitcnt lgkmcnt(0)
	v_mfma_f32_32x32x16_bf16 v[48:63], v[92:95], v[124:127], v[48:63]

.Lpb_comp_0:
	s_cmp_eq_u32 s54, 1
	s_cbranch_scc0 .Lpb_pend_0
	ds_read_b128 v[96:99], v187 offset:0
	ds_read_b128 v[100:103], v186 offset:0
	ds_read_b128 v[104:107], v185 offset:0
	ds_read_b128 v[108:111], v184 offset:0
	s_waitcnt lgkmcnt(3)
	v_mfma_f32_32x32x16_bf16 v[64:79], v[96:99], v[140:143], 0
	s_waitcnt lgkmcnt(2)
	v_mfma_f32_32x32x16_bf16 v[64:79], v[100:103], v[136:139], v[64:79]
	s_waitcnt lgkmcnt(1)
	v_mfma_f32_32x32x16_bf16 v[64:79], v[104:107], v[132:135], v[64:79]
	s_waitcnt lgkmcnt(0)
	v_mfma_f32_32x32x16_bf16 v[64:79], v[108:111], v[128:131], v[64:79]
	ds_read_b128 v[96:99], v187 offset:8192
	ds_read_b128 v[100:103], v186 offset:8192
	ds_read_b128 v[104:107], v185 offset:8192
	ds_read_b128 v[108:111], v184 offset:8192
	ds_read_b64_tr_b16 v[112:113], v172 offset:0
	ds_read_b64_tr_b16 v[114:115], v192 offset:0
	ds_read_b64_tr_b16 v[116:117], v173 offset:0
	ds_read_b64_tr_b16 v[118:119], v193 offset:0
	ds_read_b64_tr_b16 v[120:121], v174 offset:0
	ds_read_b64_tr_b16 v[122:123], v194 offset:0
	ds_read_b64_tr_b16 v[124:125], v175 offset:0
	ds_read_b64_tr_b16 v[126:127], v197 offset:0
	s_cmp_lt_i32 s54, s29
	s_cbranch_scc0 .Lpb_nv_0a
	s_add_i32 m0, s38, 0x10000
	s_nop 0
	global_load_lds_dwordx4 v166, s[58:59]
	s_add_i32 m0, s57, 0x10000
	s_nop 0
	global_load_lds_dwordx4 v170, s[58:59]
	s_add_u32 s58, s58, 0x10000
	s_addc_u32 s59, s59, 0

.Lpb_nk_0a:
	v_exp_f32_e32 v64, v64
	v_exp_f32_e32 v65, v65
	v_exp_f32_e32 v66, v66
	v_exp_f32_e32 v67, v67
	v_pk_add_f32 v[188:189], v[188:189], v[64:65]
	v_pk_add_f32 v[190:191], v[190:191], v[66:67]
	v_exp_f32_e32 v68, v68
	v_exp_f32_e32 v69, v69
	v_exp_f32_e32 v70, v70
	v_exp_f32_e32 v71, v71
	v_pk_add_f32 v[188:189], v[188:189], v[68:69]
	v_pk_add_f32 v[190:191], v[190:191], v[70:71]
	v_exp_f32_e32 v72, v72
	v_exp_f32_e32 v73, v73
	v_exp_f32_e32 v74, v74
	v_exp_f32_e32 v75, v75
	v_pk_add_f32 v[188:189], v[188:189], v[72:73]
	v_pk_add_f32 v[190:191], v[190:191], v[74:75]
	v_exp_f32_e32 v76, v76
	v_exp_f32_e32 v77, v77
	v_exp_f32_e32 v78, v78
	v_exp_f32_e32 v79, v79
	v_pk_add_f32 v[188:189], v[188:189], v[76:77]
	v_pk_add_f32 v[190:191], v[190:191], v[78:79]
	v_cvt_pk_bf16_f32 v80, v64, v65
	v_cvt_pk_bf16_f32 v81, v66, v67
	v_cvt_pk_bf16_f32 v82, v68, v69
	v_cvt_pk_bf16_f32 v83, v70, v71
	v_cvt_pk_bf16_f32 v84, v72, v73
	v_cvt_pk_bf16_f32 v85, v74, v75
	v_cvt_pk_bf16_f32 v86, v76, v77
	v_cvt_pk_bf16_f32 v87, v78, v79
	s_branch .Lpb_h1_0
.Lpb_pend_0:
	ds_read_b128 v[96:99], v187 offset:0
	ds_read_b128 v[100:103], v186 offset:0
	ds_read_b128 v[104:107], v185 offset:0
	ds_read_b128 v[108:111], v184 offset:0
	s_waitcnt lgkmcnt(3)
	v_mfma_f32_32x32x16_bf16 v[64:79], v[96:99], v[140:143], 0
	s_waitcnt lgkmcnt(2)
	v_mfma_f32_32x32x16_bf16 v[64:79], v[100:103], v[136:139], v[64:79]
	s_waitcnt lgkmcnt(1)
	v_mfma_f32_32x32x16_bf16 v[64:79], v[104:107], v[132:135], v[64:79]
	s_waitcnt lgkmcnt(0)
	v_mfma_f32_32x32x16_bf16 v[64:79], v[108:111], v[128:131], v[64:79]
	ds_read_b128 v[96:99], v187 offset:8192
	ds_read_b128 v[100:103], v186 offset:8192
	ds_read_b128 v[104:107], v185 offset:8192
	ds_read_b128 v[108:111], v184 offset:8192
	v_mfma_f32_32x32x16_bf16 v[198:213], v[88:91], v[112:115], v[198:213]
	ds_read_b64_tr_b16 v[112:113], v172 offset:45056
	ds_read_b64_tr_b16 v[114:115], v192 offset:45056
	s_cmp_lt_i32 s54, s29
	s_cbranch_scc0 .Lpb_nv_0b
	s_add_i32 m0, s38, 0x10000
	s_nop 0
	global_load_lds_dwordx4 v166, s[58:59]
	s_add_i32 m0, s57, 0x10000
	s_nop 0
	global_load_lds_dwordx4 v170, s[58:59]
	s_add_u32 s58, s58, 0x10000
	s_addc_u32 s59, s59, 0
.Lpb_nv_0b:
	v_mfma_f32_32x32x16_bf16 v[214:229], v[88:91], v[116:119], v[214:229]
	ds_read_b64_tr_b16 v[116:117], v173 offset:45056
	ds_read_b64_tr_b16 v[118:119], v193 offset:45056
	s_cmp_gt_i32 s54, s53
	s_cbranch_scc1 .Lpb_nk_0b
	s_add_i32 m0, s38, 0x8000
	s_nop 0
	global_load_lds_dwordx4 v166, s[24:25]
	s_add_i32 m0, s57, 0x8000
	s_nop 0
	global_load_lds_dwordx4 v170, s[24:25]
	s_add_u32 s24, s24, 0x10000
	s_addc_u32 s25, s25, 0
.Lpb_nk_0b:
	v_mfma_f32_32x32x16_bf16 v[230:245], v[88:91], v[120:123], v[230:245]
	ds_read_b64_tr_b16 v[120:121], v174 offset:45056
	ds_read_b64_tr_b16 v[122:123], v194 offset:45056
	v_exp_f32_e32 v64, v64
	v_exp_f32_e32 v65, v65
	v_exp_f32_e32 v66, v66
	v_exp_f32_e32 v67, v67
	v_pk_add_f32 v[188:189], v[188:189], v[64:65]
	v_pk_add_f32 v[190:191], v[190:191], v[66:67]
	v_mfma_f32_32x32x16_bf16 v[144:159], v[88:91], v[124:127], v[144:159]
	ds_read_b64_tr_b16 v[124:125], v175 offset:45056
	ds_read_b64_tr_b16 v[126:127], v197 offset:45056
	v_exp_f32_e32 v68, v68
	v_exp_f32_e32 v69, v69
	v_exp_f32_e32 v70, v70
	v_exp_f32_e32 v71, v71
	v_pk_add_f32 v[188:189], v[188:189], v[68:69]
	v_pk_add_f32 v[190:191], v[190:191], v[70:71]
	s_waitcnt lgkmcnt(6)
	v_mfma_f32_32x32x16_bf16 v[198:213], v[92:95], v[112:115], v[198:213]
	ds_read_b64_tr_b16 v[112:113], v172 offset:0
	ds_read_b64_tr_b16 v[114:115], v192 offset:0
	v_exp_f32_e32 v72, v72
	v_exp_f32_e32 v73, v73
	v_exp_f32_e32 v74, v74
	v_exp_f32_e32 v75, v75
	v_pk_add_f32 v[188:189], v[188:189], v[72:73]
	v_pk_add_f32 v[190:191], v[190:191], v[74:75]
	s_waitcnt lgkmcnt(6)
	v_mfma_f32_32x32x16_bf16 v[214:229], v[92:95], v[116:119], v[214:229]
	ds_read_b64_tr_b16 v[116:117], v173 offset:0
	ds_read_b64_tr_b16 v[118:119], v193 offset:0
	v_exp_f32_e32 v76, v76
	v_exp_f32_e32 v77, v77
	v_exp_f32_e32 v78, v78
	v_exp_f32_e32 v79, v79
	v_pk_add_f32 v[188:189], v[188:189], v[76:77]
	v_pk_add_f32 v[190:191], v[190:191], v[78:79]
	s_waitcnt lgkmcnt(6)
	v_mfma_f32_32x32x16_bf16 v[230:245], v[92:95], v[120:123], v[230:245]
	ds_read_b64_tr_b16 v[120:121], v174 offset:0
	ds_read_b64_tr_b16 v[122:123], v194 offset:0
	v_cvt_pk_bf16_f32 v80, v64, v65
	v_cvt_pk_bf16_f32 v81, v66, v67
	v_cvt_pk_bf16_f32 v82, v68, v69
	v_cvt_pk_bf16_f32 v83, v70, v71
	s_waitcnt lgkmcnt(6)
	v_mfma_f32_32x32x16_bf16 v[144:159], v[92:95], v[124:127], v[144:159]
	ds_read_b64_tr_b16 v[124:125], v175 offset:0
	ds_read_b64_tr_b16 v[126:127], v197 offset:0
	v_cvt_pk_bf16_f32 v84, v72, v73
	v_cvt_pk_bf16_f32 v85, v74, v75
	v_cvt_pk_bf16_f32 v86, v76, v77
	v_cvt_pk_bf16_f32 v87, v78, v79
.Lpb_h1_0:
	s_waitcnt lgkmcnt(11)
	v_mfma_f32_32x32x16_bf16 v[64:79], v[96:99], v[140:143], 0
	s_waitcnt lgkmcnt(10)
	v_mfma_f32_32x32x16_bf16 v[64:79], v[100:103], v[136:139], v[64:79]
	s_waitcnt lgkmcnt(9)
	v_mfma_f32_32x32x16_bf16 v[64:79], v[104:107], v[132:135], v[64:79]
	s_waitcnt lgkmcnt(8)
	v_mfma_f32_32x32x16_bf16 v[64:79], v[108:111], v[128:131], v[64:79]
	s_waitcnt lgkmcnt(6)
	v_mfma_f32_32x32x16_bf16 v[198:213], v[80:83], v[112:115], v[198:213]
	ds_read_b64_tr_b16 v[112:113], v172 offset:4096
	ds_read_b64_tr_b16 v[114:115], v192 offset:4096
	s_waitcnt lgkmcnt(6)
	v_mfma_f32_32x32x16_bf16 v[214:229], v[80:83], v[116:119], v[214:229]
	ds_read_b64_tr_b16 v[116:117], v173 offset:4096
	ds_read_b64_tr_b16 v[118:119], v193 offset:4096
	s_waitcnt lgkmcnt(6)
	v_mfma_f32_32x32x16_bf16 v[230:245], v[80:83], v[120:123], v[230:245]
	ds_read_b64_tr_b16 v[120:121], v174 offset:4096
	ds_read_b64_tr_b16 v[122:123], v194 offset:4096
	v_exp_f32_e32 v64, v64
	v_exp_f32_e32 v65, v65
	v_exp_f32_e32 v66, v66
	v_exp_f32_e32 v67, v67
	v_pk_add_f32 v[188:189], v[188:189], v[64:65]
	v_pk_add_f32 v[190:191], v[190:191], v[66:67]
	s_waitcnt lgkmcnt(6)
	v_mfma_f32_32x32x16_bf16 v[144:159], v[80:83], v[124:127], v[144:159]
	ds_read_b64_tr_b16 v[124:125], v175 offset:4096
	ds_read_b64_tr_b16 v[126:127], v197 offset:4096
	v_exp_f32_e32 v68, v68
	v_exp_f32_e32 v69, v69
	v_exp_f32_e32 v70, v70
	v_exp_f32_e32 v71, v71
	v_pk_add_f32 v[188:189], v[188:189], v[68:69]
	v_pk_add_f32 v[190:191], v[190:191], v[70:71]
	s_waitcnt lgkmcnt(6)
	v_mfma_f32_32x32x16_bf16 v[198:213], v[84:87], v[112:115], v[198:213]
	ds_read_b64_tr_b16 v[112:113], v172 offset:8192
	ds_read_b64_tr_b16 v[114:115], v192 offset:8192
	v_exp_f32_e32 v72, v72
	v_exp_f32_e32 v73, v73
	v_exp_f32_e32 v74, v74
	v_exp_f32_e32 v75, v75
	v_pk_add_f32 v[188:189], v[188:189], v[72:73]
	v_pk_add_f32 v[190:191], v[190:191], v[74:75]
	s_waitcnt lgkmcnt(6)
	v_mfma_f32_32x32x16_bf16 v[214:229], v[84:87], v[116:119], v[214:229]
	ds_read_b64_tr_b16 v[116:117], v173 offset:8192
	ds_read_b64_tr_b16 v[118:119], v193 offset:8192
	v_exp_f32_e32 v76, v76
	v_exp_f32_e32 v77, v77
	v_exp_f32_e32 v78, v78
	v_exp_f32_e32 v79, v79
	v_pk_add_f32 v[188:189], v[188:189], v[76:77]
	v_pk_add_f32 v[190:191], v[190:191], v[78:79]
	s_waitcnt lgkmcnt(6)
	v_mfma_f32_32x32x16_bf16 v[230:245], v[84:87], v[120:123], v[230:245]
	ds_read_b64_tr_b16 v[120:121], v174 offset:8192
	ds_read_b64_tr_b16 v[122:123], v194 offset:8192
	v_cvt_pk_bf16_f32 v88, v64, v65
	v_cvt_pk_bf16_f32 v89, v66, v67
	v_cvt_pk_bf16_f32 v90, v68, v69
	v_cvt_pk_bf16_f32 v91, v70, v71
	s_waitcnt lgkmcnt(6)
	v_mfma_f32_32x32x16_bf16 v[144:159], v[84:87], v[124:127], v[144:159]
	ds_read_b64_tr_b16 v[124:125], v175 offset:8192
	ds_read_b64_tr_b16 v[126:127], v197 offset:8192
	v_cvt_pk_bf16_f32 v92, v72, v73
	v_cvt_pk_bf16_f32 v93, v74, v75
	v_cvt_pk_bf16_f32 v94, v76, v77
	v_cvt_pk_bf16_f32 v95, v78, v79
	s_cmp_lt_i32 s54, vcc_lo
	s_cbranch_scc1 .Lpb_next_0
	s_nop 1
	s_waitcnt lgkmcnt(6)
	v_mfma_f32_32x32x16_bf16 v[198:213], v[88:91], v[112:115], v[198:213]
	ds_read_b64_tr_b16 v[112:113], v172 offset:12288
	ds_read_b64_tr_b16 v[114:115], v192 offset:12288
	s_waitcnt lgkmcnt(6)
	v_mfma_f32_32x32x16_bf16 v[214:229], v[88:91], v[116:119], v[214:229]
	ds_read_b64_tr_b16 v[116:117], v173 offset:12288
	ds_read_b64_tr_b16 v[118:119], v193 offset:12288
	s_waitcnt lgkmcnt(6)
	v_mfma_f32_32x32x16_bf16 v[230:245], v[88:91], v[120:123], v[230:245]
	ds_read_b64_tr_b16 v[120:121], v174 offset:12288
	ds_read_b64_tr_b16 v[122:123], v194 offset:12288
	s_waitcnt lgkmcnt(6)
	v_mfma_f32_32x32x16_bf16 v[144:159], v[88:91], v[124:127], v[144:159]
	ds_read_b64_tr_b16 v[124:125], v175 offset:12288
	ds_read_b64_tr_b16 v[126:127], v197 offset:12288
	s_waitcnt lgkmcnt(6)
	v_mfma_f32_32x32x16_bf16 v[198:213], v[92:95], v[112:115], v[198:213]
	s_waitcnt lgkmcnt(4)
	v_mfma_f32_32x32x16_bf16 v[214:229], v[92:95], v[116:119], v[214:229]
	s_waitcnt lgkmcnt(2)
	v_mfma_f32_32x32x16_bf16 v[230:245], v[92:95], v[120:123], v[230:245]
	s_waitcnt lgkmcnt(0)
	v_mfma_f32_32x32x16_bf16 v[144:159], v[92:95], v[124:127], v[144:159]

.Lpb_comp_1:
	ds_read_b128 v[96:99], v187 offset:16384
	ds_read_b128 v[100:103], v186 offset:16384
	ds_read_b128 v[104:107], v185 offset:16384
	ds_read_b128 v[108:111], v184 offset:16384
	s_waitcnt lgkmcnt(3)
	v_mfma_f32_32x32x16_bf16 v[64:79], v[96:99], v[140:143], 0
	s_waitcnt lgkmcnt(2)
	v_mfma_f32_32x32x16_bf16 v[64:79], v[100:103], v[136:139], v[64:79]
	s_waitcnt lgkmcnt(1)
	v_mfma_f32_32x32x16_bf16 v[64:79], v[104:107], v[132:135], v[64:79]
	s_waitcnt lgkmcnt(0)
	v_mfma_f32_32x32x16_bf16 v[64:79], v[108:111], v[128:131], v[64:79]
	ds_read_b128 v[96:99], v187 offset:24576
	ds_read_b128 v[100:103], v186 offset:24576
	ds_read_b128 v[104:107], v185 offset:24576
	ds_read_b128 v[108:111], v184 offset:24576
	v_mfma_f32_32x32x16_bf16 v[198:213], v[88:91], v[112:115], v[198:213]
	ds_read_b64_tr_b16 v[112:113], v172 offset:12288
	ds_read_b64_tr_b16 v[114:115], v192 offset:12288
	s_cmp_lt_i32 s54, s29
	s_cbranch_scc0 .Lpb_nv_1b
	s_add_i32 m0, s38, 0x14000
	s_nop 0
	global_load_lds_dwordx4 v166, s[58:59]
	s_add_i32 m0, s57, 0x14000
	s_nop 0
	global_load_lds_dwordx4 v170, s[58:59]
	s_add_u32 s58, s58, 0x10000
	s_addc_u32 s59, s59, 0
.Lpb_nv_1b:
	v_mfma_f32_32x32x16_bf16 v[214:229], v[88:91], v[116:119], v[214:229]
	ds_read_b64_tr_b16 v[116:117], v173 offset:12288
	ds_read_b64_tr_b16 v[118:119], v193 offset:12288
	s_cmp_gt_i32 s54, s53
	s_cbranch_scc1 .Lpb_nk_1b
	s_add_i32 m0, s38, 0x0
	s_nop 0
	global_load_lds_dwordx4 v166, s[24:25]
	s_add_i32 m0, s57, 0x0
	s_nop 0
	global_load_lds_dwordx4 v170, s[24:25]
	s_add_u32 s24, s24, 0x10000
	s_addc_u32 s25, s25, 0
.Lpb_nk_1b:
	v_mfma_f32_32x32x16_bf16 v[230:245], v[88:91], v[120:123], v[230:245]
	ds_read_b64_tr_b16 v[120:121], v174 offset:12288
	ds_read_b64_tr_b16 v[122:123], v194 offset:12288
	v_exp_f32_e32 v64, v64
	v_exp_f32_e32 v65, v65
	v_exp_f32_e32 v66, v66
	v_exp_f32_e32 v67, v67
	v_pk_add_f32 v[188:189], v[188:189], v[64:65]
	v_pk_add_f32 v[190:191], v[190:191], v[66:67]
	v_mfma_f32_32x32x16_bf16 v[144:159], v[88:91], v[124:127], v[144:159]
	ds_read_b64_tr_b16 v[124:125], v175 offset:12288
	ds_read_b64_tr_b16 v[126:127], v197 offset:12288
	v_exp_f32_e32 v68, v68
	v_exp_f32_e32 v69, v69
	v_exp_f32_e32 v70, v70
	v_exp_f32_e32 v71, v71
	v_pk_add_f32 v[188:189], v[188:189], v[68:69]
	v_pk_add_f32 v[190:191], v[190:191], v[70:71]
	s_waitcnt lgkmcnt(6)
	v_mfma_f32_32x32x16_bf16 v[198:213], v[92:95], v[112:115], v[198:213]
	ds_read_b64_tr_b16 v[112:113], v172 offset:16384
	ds_read_b64_tr_b16 v[114:115], v192 offset:16384
	v_exp_f32_e32 v72, v72
	v_exp_f32_e32 v73, v73
	v_exp_f32_e32 v74, v74
	v_exp_f32_e32 v75, v75
	v_pk_add_f32 v[188:189], v[188:189], v[72:73]
	v_pk_add_f32 v[190:191], v[190:191], v[74:75]
	s_waitcnt lgkmcnt(6)
	v_mfma_f32_32x32x16_bf16 v[214:229], v[92:95], v[116:119], v[214:229]
	ds_read_b64_tr_b16 v[116:117], v173 offset:16384
	ds_read_b64_tr_b16 v[118:119], v193 offset:16384
	v_exp_f32_e32 v76, v76
	v_exp_f32_e32 v77, v77
	v_exp_f32_e32 v78, v78
	v_exp_f32_e32 v79, v79
	v_pk_add_f32 v[188:189], v[188:189], v[76:77]
	v_pk_add_f32 v[190:191], v[190:191], v[78:79]
	s_waitcnt lgkmcnt(6)
	v_mfma_f32_32x32x16_bf16 v[230:245], v[92:95], v[120:123], v[230:245]
	ds_read_b64_tr_b16 v[120:121], v174 offset:16384
	ds_read_b64_tr_b16 v[122:123], v194 offset:16384
	v_cvt_pk_bf16_f32 v80, v64, v65
	v_cvt_pk_bf16_f32 v81, v66, v67
	v_cvt_pk_bf16_f32 v82, v68, v69
	v_cvt_pk_bf16_f32 v83, v70, v71
	s_waitcnt lgkmcnt(6)
	v_mfma_f32_32x32x16_bf16 v[144:159], v[92:95], v[124:127], v[144:159]
	ds_read_b64_tr_b16 v[124:125], v175 offset:16384
	ds_read_b64_tr_b16 v[126:127], v197 offset:16384
	v_cvt_pk_bf16_f32 v84, v72, v73
	v_cvt_pk_bf16_f32 v85, v74, v75
	v_cvt_pk_bf16_f32 v86, v76, v77
	v_cvt_pk_bf16_f32 v87, v78, v79
.Lpb_h1_1:
	s_waitcnt lgkmcnt(11)
	v_mfma_f32_32x32x16_bf16 v[64:79], v[96:99], v[140:143], 0
	s_waitcnt lgkmcnt(10)
	v_mfma_f32_32x32x16_bf16 v[64:79], v[100:103], v[136:139], v[64:79]
	s_waitcnt lgkmcnt(9)
	v_mfma_f32_32x32x16_bf16 v[64:79], v[104:107], v[132:135], v[64:79]
	s_waitcnt lgkmcnt(8)
	v_mfma_f32_32x32x16_bf16 v[64:79], v[108:111], v[128:131], v[64:79]
	s_waitcnt lgkmcnt(6)
	v_mfma_f32_32x32x16_bf16 v[198:213], v[80:83], v[112:115], v[198:213]
	ds_read_b64_tr_b16 v[112:113], v172 offset:20480
	ds_read_b64_tr_b16 v[114:115], v192 offset:20480
	s_waitcnt lgkmcnt(6)
	v_mfma_f32_32x32x16_bf16 v[214:229], v[80:83], v[116:119], v[214:229]
	ds_read_b64_tr_b16 v[116:117], v173 offset:20480
	ds_read_b64_tr_b16 v[118:119], v193 offset:20480
	s_waitcnt lgkmcnt(6)
	v_mfma_f32_32x32x16_bf16 v[230:245], v[80:83], v[120:123], v[230:245]
	ds_read_b64_tr_b16 v[120:121], v174 offset:20480
	ds_read_b64_tr_b16 v[122:123], v194 offset:20480
	v_exp_f32_e32 v64, v64
	v_exp_f32_e32 v65, v65
	v_exp_f32_e32 v66, v66
	v_exp_f32_e32 v67, v67
	v_pk_add_f32 v[188:189], v[188:189], v[64:65]
	v_pk_add_f32 v[190:191], v[190:191], v[66:67]
	s_waitcnt lgkmcnt(6)
	v_mfma_f32_32x32x16_bf16 v[144:159], v[80:83], v[124:127], v[144:159]
	ds_read_b64_tr_b16 v[124:125], v175 offset:20480
	ds_read_b64_tr_b16 v[126:127], v197 offset:20480
	v_exp_f32_e32 v68, v68
	v_exp_f32_e32 v69, v69
	v_exp_f32_e32 v70, v70
	v_exp_f32_e32 v71, v71
	v_pk_add_f32 v[188:189], v[188:189], v[68:69]
	v_pk_add_f32 v[190:191], v[190:191], v[70:71]
	s_waitcnt lgkmcnt(6)
	v_mfma_f32_32x32x16_bf16 v[198:213], v[84:87], v[112:115], v[198:213]
	ds_read_b64_tr_b16 v[112:113], v172 offset:24576
	ds_read_b64_tr_b16 v[114:115], v192 offset:24576
	v_exp_f32_e32 v72, v72
	v_exp_f32_e32 v73, v73
	v_exp_f32_e32 v74, v74
	v_exp_f32_e32 v75, v75
	v_pk_add_f32 v[188:189], v[188:189], v[72:73]
	v_pk_add_f32 v[190:191], v[190:191], v[74:75]
	s_waitcnt lgkmcnt(6)
	v_mfma_f32_32x32x16_bf16 v[214:229], v[84:87], v[116:119], v[214:229]
	ds_read_b64_tr_b16 v[116:117], v173 offset:24576
	ds_read_b64_tr_b16 v[118:119], v193 offset:24576
	v_exp_f32_e32 v76, v76
	v_exp_f32_e32 v77, v77
	v_exp_f32_e32 v78, v78
	v_exp_f32_e32 v79, v79
	v_pk_add_f32 v[188:189], v[188:189], v[76:77]
	v_pk_add_f32 v[190:191], v[190:191], v[78:79]
	s_waitcnt lgkmcnt(6)
	v_mfma_f32_32x32x16_bf16 v[230:245], v[84:87], v[120:123], v[230:245]
	ds_read_b64_tr_b16 v[120:121], v174 offset:24576
	ds_read_b64_tr_b16 v[122:123], v194 offset:24576
	v_cvt_pk_bf16_f32 v88, v64, v65
	v_cvt_pk_bf16_f32 v89, v66, v67
	v_cvt_pk_bf16_f32 v90, v68, v69
	v_cvt_pk_bf16_f32 v91, v70, v71
	s_waitcnt lgkmcnt(6)
	v_mfma_f32_32x32x16_bf16 v[144:159], v[84:87], v[124:127], v[144:159]
	ds_read_b64_tr_b16 v[124:125], v175 offset:24576
	ds_read_b64_tr_b16 v[126:127], v197 offset:24576
	v_cvt_pk_bf16_f32 v92, v72, v73
	v_cvt_pk_bf16_f32 v93, v74, v75
	v_cvt_pk_bf16_f32 v94, v76, v77
	v_cvt_pk_bf16_f32 v95, v78, v79
	s_cmp_lt_i32 s54, vcc_lo
	s_cbranch_scc1 .Lpb_next_1
	s_nop 1
	s_waitcnt lgkmcnt(6)
	v_mfma_f32_32x32x16_bf16 v[198:213], v[88:91], v[112:115], v[198:213]
	ds_read_b64_tr_b16 v[112:113], v172 offset:28672
	ds_read_b64_tr_b16 v[114:115], v192 offset:28672
	s_waitcnt lgkmcnt(6)
	v_mfma_f32_32x32x16_bf16 v[214:229], v[88:91], v[116:119], v[214:229]
	ds_read_b64_tr_b16 v[116:117], v173 offset:28672
	ds_read_b64_tr_b16 v[118:119], v193 offset:28672
	s_waitcnt lgkmcnt(6)
	v_mfma_f32_32x32x16_bf16 v[230:245], v[88:91], v[120:123], v[230:245]
	ds_read_b64_tr_b16 v[120:121], v174 offset:28672
	ds_read_b64_tr_b16 v[122:123], v194 offset:28672
	s_waitcnt lgkmcnt(6)
	v_mfma_f32_32x32x16_bf16 v[144:159], v[88:91], v[124:127], v[144:159]
	ds_read_b64_tr_b16 v[124:125], v175 offset:28672
	ds_read_b64_tr_b16 v[126:127], v197 offset:28672
	s_waitcnt lgkmcnt(6)
	v_mfma_f32_32x32x16_bf16 v[198:213], v[92:95], v[112:115], v[198:213]
	s_waitcnt lgkmcnt(4)
	v_mfma_f32_32x32x16_bf16 v[214:229], v[92:95], v[116:119], v[214:229]
	s_waitcnt lgkmcnt(2)
	v_mfma_f32_32x32x16_bf16 v[230:245], v[92:95], v[120:123], v[230:245]
	s_waitcnt lgkmcnt(0)
	v_mfma_f32_32x32x16_bf16 v[144:159], v[92:95], v[124:127], v[144:159]

.Lpb_comp_2:
	ds_read_b128 v[96:99], v187 offset:32768
	ds_read_b128 v[100:103], v186 offset:32768
	ds_read_b128 v[104:107], v185 offset:32768
	ds_read_b128 v[108:111], v184 offset:32768
	s_waitcnt lgkmcnt(3)
	v_mfma_f32_32x32x16_bf16 v[64:79], v[96:99], v[140:143], 0
	s_waitcnt lgkmcnt(2)
	v_mfma_f32_32x32x16_bf16 v[64:79], v[100:103], v[136:139], v[64:79]
	s_waitcnt lgkmcnt(1)
	v_mfma_f32_32x32x16_bf16 v[64:79], v[104:107], v[132:135], v[64:79]
	s_waitcnt lgkmcnt(0)
	v_mfma_f32_32x32x16_bf16 v[64:79], v[108:111], v[128:131], v[64:79]
	ds_read_b128 v[96:99], v187 offset:40960
	ds_read_b128 v[100:103], v186 offset:40960
	ds_read_b128 v[104:107], v185 offset:40960
	ds_read_b128 v[108:111], v184 offset:40960
	v_mfma_f32_32x32x16_bf16 v[198:213], v[88:91], v[112:115], v[198:213]
	ds_read_b64_tr_b16 v[112:113], v172 offset:28672
	ds_read_b64_tr_b16 v[114:115], v192 offset:28672
	s_cmp_lt_i32 s54, s29
	s_cbranch_scc0 .Lpb_nv_2b
	s_add_i32 m0, s38, 0xc000
	s_nop 0
	global_load_lds_dwordx4 v166, s[58:59]
	s_add_i32 m0, s57, 0xc000
	s_nop 0
	global_load_lds_dwordx4 v170, s[58:59]
	s_add_u32 s58, s58, 0x10000
	s_addc_u32 s59, s59, 0
.Lpb_nv_2b:
	v_mfma_f32_32x32x16_bf16 v[214:229], v[88:91], v[116:119], v[214:229]
	ds_read_b64_tr_b16 v[116:117], v173 offset:28672
	ds_read_b64_tr_b16 v[118:119], v193 offset:28672
	s_cmp_gt_i32 s54, s53
	s_cbranch_scc1 .Lpb_nk_2b
	s_add_i32 m0, s38, 0x4000
	s_nop 0
	global_load_lds_dwordx4 v166, s[24:25]
	s_add_i32 m0, s57, 0x4000
	s_nop 0
	global_load_lds_dwordx4 v170, s[24:25]
	s_add_u32 s24, s24, 0x10000
	s_addc_u32 s25, s25, 0
.Lpb_nk_2b:
	v_mfma_f32_32x32x16_bf16 v[230:245], v[88:91], v[120:123], v[230:245]
	ds_read_b64_tr_b16 v[120:121], v174 offset:28672
	ds_read_b64_tr_b16 v[122:123], v194 offset:28672
	v_exp_f32_e32 v64, v64
	v_exp_f32_e32 v65, v65
	v_exp_f32_e32 v66, v66
	v_exp_f32_e32 v67, v67
	v_pk_add_f32 v[188:189], v[188:189], v[64:65]
	v_pk_add_f32 v[190:191], v[190:191], v[66:67]
	v_mfma_f32_32x32x16_bf16 v[144:159], v[88:91], v[124:127], v[144:159]
	ds_read_b64_tr_b16 v[124:125], v175 offset:28672
	ds_read_b64_tr_b16 v[126:127], v197 offset:28672
	v_exp_f32_e32 v68, v68
	v_exp_f32_e32 v69, v69
	v_exp_f32_e32 v70, v70
	v_exp_f32_e32 v71, v71
	v_pk_add_f32 v[188:189], v[188:189], v[68:69]
	v_pk_add_f32 v[190:191], v[190:191], v[70:71]
	s_waitcnt lgkmcnt(6)
	v_mfma_f32_32x32x16_bf16 v[198:213], v[92:95], v[112:115], v[198:213]
	ds_read_b64_tr_b16 v[112:113], v172 offset:32768
	ds_read_b64_tr_b16 v[114:115], v192 offset:32768
	v_exp_f32_e32 v72, v72
	v_exp_f32_e32 v73, v73
	v_exp_f32_e32 v74, v74
	v_exp_f32_e32 v75, v75
	v_pk_add_f32 v[188:189], v[188:189], v[72:73]
	v_pk_add_f32 v[190:191], v[190:191], v[74:75]
	s_waitcnt lgkmcnt(6)
	v_mfma_f32_32x32x16_bf16 v[214:229], v[92:95], v[116:119], v[214:229]
	ds_read_b64_tr_b16 v[116:117], v173 offset:32768
	ds_read_b64_tr_b16 v[118:119], v193 offset:32768
	v_exp_f32_e32 v76, v76
	v_exp_f32_e32 v77, v77
	v_exp_f32_e32 v78, v78
	v_exp_f32_e32 v79, v79
	v_pk_add_f32 v[188:189], v[188:189], v[76:77]
	v_pk_add_f32 v[190:191], v[190:191], v[78:79]
	s_waitcnt lgkmcnt(6)
	v_mfma_f32_32x32x16_bf16 v[230:245], v[92:95], v[120:123], v[230:245]
	ds_read_b64_tr_b16 v[120:121], v174 offset:32768
	ds_read_b64_tr_b16 v[122:123], v194 offset:32768
	v_cvt_pk_bf16_f32 v80, v64, v65
	v_cvt_pk_bf16_f32 v81, v66, v67
	v_cvt_pk_bf16_f32 v82, v68, v69
	v_cvt_pk_bf16_f32 v83, v70, v71
	s_waitcnt lgkmcnt(6)
	v_mfma_f32_32x32x16_bf16 v[144:159], v[92:95], v[124:127], v[144:159]
	ds_read_b64_tr_b16 v[124:125], v175 offset:32768
	ds_read_b64_tr_b16 v[126:127], v197 offset:32768
	v_cvt_pk_bf16_f32 v84, v72, v73
	v_cvt_pk_bf16_f32 v85, v74, v75
	v_cvt_pk_bf16_f32 v86, v76, v77
	v_cvt_pk_bf16_f32 v87, v78, v79
.Lpb_h1_2:
	s_waitcnt lgkmcnt(11)
	v_mfma_f32_32x32x16_bf16 v[64:79], v[96:99], v[140:143], 0
	s_waitcnt lgkmcnt(10)
	v_mfma_f32_32x32x16_bf16 v[64:79], v[100:103], v[136:139], v[64:79]
	s_waitcnt lgkmcnt(9)
	v_mfma_f32_32x32x16_bf16 v[64:79], v[104:107], v[132:135], v[64:79]
	s_waitcnt lgkmcnt(8)
	v_mfma_f32_32x32x16_bf16 v[64:79], v[108:111], v[128:131], v[64:79]
	s_waitcnt lgkmcnt(6)
	v_mfma_f32_32x32x16_bf16 v[198:213], v[80:83], v[112:115], v[198:213]
	ds_read_b64_tr_b16 v[112:113], v172 offset:36864
	ds_read_b64_tr_b16 v[114:115], v192 offset:36864
	s_waitcnt lgkmcnt(6)
	v_mfma_f32_32x32x16_bf16 v[214:229], v[80:83], v[116:119], v[214:229]
	ds_read_b64_tr_b16 v[116:117], v173 offset:36864
	ds_read_b64_tr_b16 v[118:119], v193 offset:36864
	s_waitcnt lgkmcnt(6)
	v_mfma_f32_32x32x16_bf16 v[230:245], v[80:83], v[120:123], v[230:245]
	ds_read_b64_tr_b16 v[120:121], v174 offset:36864
	ds_read_b64_tr_b16 v[122:123], v194 offset:36864
	v_exp_f32_e32 v64, v64
	v_exp_f32_e32 v65, v65
	v_exp_f32_e32 v66, v66
	v_exp_f32_e32 v67, v67
	v_pk_add_f32 v[188:189], v[188:189], v[64:65]
	v_pk_add_f32 v[190:191], v[190:191], v[66:67]
	s_waitcnt lgkmcnt(6)
	v_mfma_f32_32x32x16_bf16 v[144:159], v[80:83], v[124:127], v[144:159]
	ds_read_b64_tr_b16 v[124:125], v175 offset:36864
	ds_read_b64_tr_b16 v[126:127], v197 offset:36864
	v_exp_f32_e32 v68, v68
	v_exp_f32_e32 v69, v69
	v_exp_f32_e32 v70, v70
	v_exp_f32_e32 v71, v71
	v_pk_add_f32 v[188:189], v[188:189], v[68:69]
	v_pk_add_f32 v[190:191], v[190:191], v[70:71]
	s_waitcnt lgkmcnt(6)
	v_mfma_f32_32x32x16_bf16 v[198:213], v[84:87], v[112:115], v[198:213]
	ds_read_b64_tr_b16 v[112:113], v172 offset:40960
	ds_read_b64_tr_b16 v[114:115], v192 offset:40960
	v_exp_f32_e32 v72, v72
	v_exp_f32_e32 v73, v73
	v_exp_f32_e32 v74, v74
	v_exp_f32_e32 v75, v75
	v_pk_add_f32 v[188:189], v[188:189], v[72:73]
	v_pk_add_f32 v[190:191], v[190:191], v[74:75]
	s_waitcnt lgkmcnt(6)
	v_mfma_f32_32x32x16_bf16 v[214:229], v[84:87], v[116:119], v[214:229]
	ds_read_b64_tr_b16 v[116:117], v173 offset:40960
	ds_read_b64_tr_b16 v[118:119], v193 offset:40960
	v_exp_f32_e32 v76, v76
	v_exp_f32_e32 v77, v77
	v_exp_f32_e32 v78, v78
	v_exp_f32_e32 v79, v79
	v_pk_add_f32 v[188:189], v[188:189], v[76:77]
	v_pk_add_f32 v[190:191], v[190:191], v[78:79]
	s_waitcnt lgkmcnt(6)
	v_mfma_f32_32x32x16_bf16 v[230:245], v[84:87], v[120:123], v[230:245]
	ds_read_b64_tr_b16 v[120:121], v174 offset:40960
	ds_read_b64_tr_b16 v[122:123], v194 offset:40960
	v_cvt_pk_bf16_f32 v88, v64, v65
	v_cvt_pk_bf16_f32 v89, v66, v67
	v_cvt_pk_bf16_f32 v90, v68, v69
	v_cvt_pk_bf16_f32 v91, v70, v71
	s_waitcnt lgkmcnt(6)
	v_mfma_f32_32x32x16_bf16 v[144:159], v[84:87], v[124:127], v[144:159]
	ds_read_b64_tr_b16 v[124:125], v175 offset:40960
	ds_read_b64_tr_b16 v[126:127], v197 offset:40960
	v_cvt_pk_bf16_f32 v92, v72, v73
	v_cvt_pk_bf16_f32 v93, v74, v75
	v_cvt_pk_bf16_f32 v94, v76, v77
	v_cvt_pk_bf16_f32 v95, v78, v79
	s_cmp_lt_i32 s54, vcc_lo
	s_cbranch_scc1 .Lpb_next_2
	s_nop 1
	s_waitcnt lgkmcnt(6)
	v_mfma_f32_32x32x16_bf16 v[198:213], v[88:91], v[112:115], v[198:213]
	ds_read_b64_tr_b16 v[112:113], v172 offset:45056
	ds_read_b64_tr_b16 v[114:115], v192 offset:45056
	s_waitcnt lgkmcnt(6)
	v_mfma_f32_32x32x16_bf16 v[214:229], v[88:91], v[116:119], v[214:229]
	ds_read_b64_tr_b16 v[116:117], v173 offset:45056
	ds_read_b64_tr_b16 v[118:119], v193 offset:45056
	s_waitcnt lgkmcnt(6)
	v_mfma_f32_32x32x16_bf16 v[230:245], v[88:91], v[120:123], v[230:245]
	ds_read_b64_tr_b16 v[120:121], v174 offset:45056
	ds_read_b64_tr_b16 v[122:123], v194 offset:45056
	s_waitcnt lgkmcnt(6)
	v_mfma_f32_32x32x16_bf16 v[144:159], v[88:91], v[124:127], v[144:159]
	ds_read_b64_tr_b16 v[124:125], v175 offset:45056
	ds_read_b64_tr_b16 v[126:127], v197 offset:45056
	s_waitcnt lgkmcnt(6)
	v_mfma_f32_32x32x16_bf16 v[198:213], v[92:95], v[112:115], v[198:213]
	s_waitcnt lgkmcnt(4)
	v_mfma_f32_32x32x16_bf16 v[214:229], v[92:95], v[116:119], v[214:229]
	s_waitcnt lgkmcnt(2)
	v_mfma_f32_32x32x16_bf16 v[230:245], v[92:95], v[120:123], v[230:245]
	s_waitcnt lgkmcnt(0)
	v_mfma_f32_32x32x16_bf16 v[144:159], v[92:95], v[124:127], v[144:159]
